# L2 write-back skipped at seams 7 and 8 when the XCC hosts exactly the workgroups of one id residue (guarded); final norm hand-written with XCC-local rows
# speedup vs baseline: 1.0009x; 1.0009x over previous
; #define LAS __attribute__((address_space(3)))
; __device__ __forceinline__ unsigned xb_add(unsigned* p, unsigned v) { return __hip_atomic_fetch_add(p, v, __ATOMIC_RELAXED, __HIP_MEMORY_SCOPE_AGENT); }
; __device__ __forceinline__ unsigned xb_xcc_id() { return (unsigned)__builtin_amdgcn_s_getreg((3 << 11) | 20) & 0xFu; }
; __device__ __forceinline__ XcdBarrier xcd_barrier_post(unsigned* bar, volatile LAS unsigned* st) {
;     XcdBarrier b; b.bar = bar; b.x = xb_xcc_id(); b.st = st;
;     if (threadIdx.x == 0) (void)xb_add(&bar[XB_XCNT(b.x)], 1u);
;     return b;
.LBB0_3:
	s_or_b64 exec, exec, s[8:9]
	s_waitcnt lgkmcnt(0)
	s_barrier
	s_load_dword s0, s[6:7], 0xc8
	s_getreg_b32 s3, hwreg(HW_REG_XCC_ID, 0, 4)
	v_cmp_eq_u32_e64 s[96:97], 0, v0
	s_waitcnt lgkmcnt(0)
	s_mulk_i32 s0, 0xd80
	s_ashr_i32 s1, s0, 31
	s_lshl_b64 s[0:1], s[0:1], 2
	s_add_u32 s0, s4, s0
	s_addc_u32 s1, s5, s1
	s_add_u32 s78, s0, 0x4000
	s_addc_u32 s79, s1, 0
	s_and_b32 s0, s3, 15
	s_and_saveexec_b64 s[8:9], s[96:97]
	s_cbranch_execz .LBB0_6
	s_mov_b64 s[10:11], exec
	v_mbcnt_lo_u32_b32 v1, s10, 0
	v_mbcnt_hi_u32_b32 v1, s11, v1
	v_cmp_eq_u32_e32 vcc, 0, v1
	s_and_b64 s[4:5], exec, vcc
	s_mov_b64 exec, s[4:5]
	s_cbranch_execz .LBB0_6
	s_lshl_b32 s1, s0, 8
	s_bcnt1_i32_b64 s3, s[10:11]
	v_mov_b32_e32 v1, s1
	v_mov_b32_e32 v2, s3
	global_atomic_add v1, v2, s[78:79] offset:1024
	s_and_b32 s3, s2, 7
	s_lshl_b32 s3, 1, s3
	s_lshl_b32 s1, s0, 2
	v_mov_b32_e32 v1, s1
	v_mov_b32_e32 v2, s3
	global_atomic_or v1, v2, s[78:79] offset:64

; __device__ __forceinline__ unsigned xb_add(unsigned* p, unsigned v) { return __hip_atomic_fetch_add(p, v, __ATOMIC_RELAXED, __HIP_MEMORY_SCOPE_AGENT); }
; __device__ __forceinline__ void xcd_barrier(const XcdBarrier& b) {
;     ...
;         const unsigned old = xb_add(&bar[XB_XSUB(b.x)], 1u);
;         const unsigned gen = old / nloc;
;         if (old + 1u == (gen + 1u) * nloc) {
;             __builtin_amdgcn_fence(__ATOMIC_RELEASE, "agent");
;             asm volatile("s_waitcnt vmcnt(0)" ::: "memory");
;             const unsigned og = xb_add(&bar[XB_TOP], 1u);
;             const unsigned tg = og / nx;
;             if (og + 1u == (tg + 1u) * nx) xb_add(&bar[XB_TOPGEN], 1u);
.LBB0_1416:
	s_andn2_saveexec_b64 s[4:5], s[12:13]
	s_cbranch_execz .LBB0_1436
	s_mov_b64 s[12:13], exec
	v_mov_b32_e32 v20, 0x20160
	ds_read_b32 v21, v20
	s_lshl_b32 s28, s0, 2
	v_mov_b32_e32 v22, s28
	global_load_dword v22, v22, s[78:79] offset:64 sc1
	s_and_b32 s29, s2, 7
	s_lshl_b32 s29, 1, s29
	s_waitcnt vmcnt(0) lgkmcnt(0)
	v_readfirstlane_b32 s30, v21
	v_readfirstlane_b32 s31, v22
	s_lshl_b32 s30, s30, 3
	s_cmpk_lg_i32 s74, 0x100
	s_cbranch_scc1 .Lwb7_do
	s_cmp_lg_u32 s30, s74
	s_cbranch_scc1 .Lwb7_do
	s_cmp_eq_u32 s31, s29
	s_cbranch_scc1 .Lwb7_skip
.Lwb7_do:
	buffer_wbl2 sc1
	s_waitcnt lgkmcnt(0)
	s_waitcnt vmcnt(0)
.Lwb7_skip:
	v_mbcnt_lo_u32_b32 v2, s12, 0
	v_mbcnt_hi_u32_b32 v2, s13, v2
	v_cmp_eq_u32_e32 vcc, 0, v2
	s_and_saveexec_b64 s[14:15], vcc
	s_cbranch_execz .LBB0_1419
	s_bcnt1_i32_b64 s1, s[12:13]
	v_mov_b32_e32 v3, 0x3000
	v_mov_b32_e32 v4, s1
	global_atomic_add v3, v3, v4, s[78:79] offset:1024 sc0

; __device__ __forceinline__ unsigned xb_add(unsigned* p, unsigned v) { return __hip_atomic_fetch_add(p, v, __ATOMIC_RELAXED, __HIP_MEMORY_SCOPE_AGENT); }
; __device__ __forceinline__ void xcd_barrier(const XcdBarrier& b) {
;     ...
;         const unsigned old = xb_add(&bar[XB_XSUB(b.x)], 1u);
;         const unsigned gen = old / nloc;
;         if (old + 1u == (gen + 1u) * nloc) {
;             __builtin_amdgcn_fence(__ATOMIC_RELEASE, "agent");
;             asm volatile("s_waitcnt vmcnt(0)" ::: "memory");
;             const unsigned og = xb_add(&bar[XB_TOP], 1u);
;             const unsigned tg = og / nx;
;             if (og + 1u == (tg + 1u) * nx) xb_add(&bar[XB_TOPGEN], 1u);
.LBB0_1513:
	s_andn2_saveexec_b64 s[0:1], s[10:11]
	s_cbranch_execz .LBB0_1533
	s_mov_b64 s[10:11], exec
	v_mov_b32_e32 v20, 0x20160
	ds_read_b32 v21, v20
	s_lshl_b32 s28, s0, 2
	v_mov_b32_e32 v22, s28
	global_load_dword v22, v22, s[78:79] offset:64 sc1
	s_and_b32 s29, s2, 7
	s_lshl_b32 s29, 1, s29
	s_waitcnt vmcnt(0) lgkmcnt(0)
	v_readfirstlane_b32 s30, v21
	v_readfirstlane_b32 s31, v22
	s_lshl_b32 s30, s30, 3
	s_cmpk_lg_i32 s74, 0x100
	s_cbranch_scc1 .Lwb8_do
	s_cmp_lg_u32 s30, s74
	s_cbranch_scc1 .Lwb8_do
	s_cmp_eq_u32 s31, s29
	s_cbranch_scc1 .Lwb8_skip

; __device__ __forceinline__ unsigned xb_add(unsigned* p, unsigned v) { return __hip_atomic_fetch_add(p, v, __ATOMIC_RELAXED, __HIP_MEMORY_SCOPE_AGENT); }
; __device__ __forceinline__ void xcd_barrier(const XcdBarrier& b) {
;     ...
;         const unsigned old = xb_add(&bar[XB_XSUB(b.x)], 1u);
;         const unsigned gen = old / nloc;
;         if (old + 1u == (gen + 1u) * nloc) {
;             __builtin_amdgcn_fence(__ATOMIC_RELEASE, "agent");
;             asm volatile("s_waitcnt vmcnt(0)" ::: "memory");
;             const unsigned og = xb_add(&bar[XB_TOP], 1u);
;             const unsigned tg = og / nx;
;             if (og + 1u == (tg + 1u) * nx) xb_add(&bar[XB_TOPGEN], 1u);
.Lwb8_skip:
	v_mbcnt_lo_u32_b32 v2, s10, 0
	v_mbcnt_hi_u32_b32 v2, s11, v2
	v_cmp_eq_u32_e32 vcc, 0, v2
	s_and_saveexec_b64 s[12:13], vcc
	s_cbranch_execz .LBB0_1516
	s_bcnt1_i32_b64 s0, s[10:11]
	v_mov_b32_e32 v3, 0x3000
	v_mov_b32_e32 v4, s0
	global_atomic_add v3, v3, v4, s[78:79] offset:1024 sc0

; __device__ __forceinline__ void ph_final_norm(float* H, const float* __restrict__ rowss, const float* __restrict__ g, size_t gt, size_t NGT) {
;     const size_t n4 = (size_t)SEQ * DM / 4;
;     f32x4* h4 = (f32x4*)H;
;     for (size_t i0 = gt; i0 < n4; i0 += 8 * NGT) {
;         f32x4 v[8]; float rs[8];
; #pragma unroll
;         for (int k = 0; k < 8; ++k) { const size_t i = i0 + k * NGT; v[k] = h4[i]; rs[k] = rowss[i >> 10]; }
; #pragma unroll
;         for (int k = 0; k < 8; ++k) { const size_t i = i0 + k * NGT; const f32x4 gg = ((const f32x4*)g)[i & 1023]; h4[i] = v[k] * rsqrtf(rs[k] * (1.f / DM) + EPS) * gg; }
;     }
; }
.LBB0_1534:
	s_cmp_lt_i32 s76, 10
	s_cselect_b64 s[0:1], -1, 0
	s_and_b64 s[0:1], s[0:1], s[6:7]
	s_andn2_b64 vcc, exec, s[0:1]
	s_cbranch_vccnz .LBB0_1538
	s_cmpk_lg_i32 s74, 0x100
	s_cbranch_scc1 .Lp9_orig
	s_load_dwordx2 s[0:1], s[92:93], 0xb8
	s_load_dwordx4 s[16:19], s[92:93], 0xa8
	s_and_b32 s22, s2, 7
	s_lshr_b32 s23, s2, 3
	s_lshl_b32 s22, s22, 11
	s_lshl_b32 s23, s23, 6
	s_add_i32 s22, s22, s23
	v_lshlrev_b32_e32 v1, 4, v0
	v_mov_b32_e32 v10, 0x358637bd
	v_mov_b32_e32 v3, 0
	s_waitcnt lgkmcnt(0)
	global_load_dwordx4 v[6:9], v1, s[16:17]
	v_add_u32_e32 v2, 0x2000, v1
	global_load_dwordx4 v[110:113], v2, s[16:17]
	s_lshl_b32 s23, s22, 2
	s_add_u32 s20, s0, s23
	s_addc_u32 s21, s1, 0
	s_add_u32 s20, s20, 0x60000
	s_addc_u32 s21, s21, 0
	s_lshr_b32 s25, s22, 18
	s_lshl_b32 s24, s22, 14
	s_add_u32 s24, s18, s24
	s_addc_u32 s25, s19, s25
	s_mov_b32 s22, 0
.Lp9_loop:
	global_load_dword v12, v3, s[20:21] offset:0 sc1
	global_load_dword v14, v3, s[20:21] offset:4 sc1
	global_load_dword v16, v3, s[20:21] offset:8 sc1
	global_load_dword v18, v3, s[20:21] offset:12 sc1
	global_load_dword v20, v3, s[20:21] offset:16 sc1
	global_load_dword v22, v3, s[20:21] offset:20 sc1
	global_load_dword v24, v3, s[20:21] offset:24 sc1
	global_load_dword v26, v3, s[20:21] offset:28 sc1
	s_mov_b64 s[26:27], s[24:25]
	global_load_dwordx4 v[44:47], v1, s[26:27]
	s_add_u32 s26, s26, 0x2000
	s_addc_u32 s27, s27, 0
	global_load_dwordx4 v[48:51], v1, s[26:27]
	s_add_u32 s26, s26, 0x2000
	s_addc_u32 s27, s27, 0
	global_load_dwordx4 v[52:55], v1, s[26:27]
	s_add_u32 s26, s26, 0x2000
	s_addc_u32 s27, s27, 0
	global_load_dwordx4 v[56:59], v1, s[26:27]
	s_add_u32 s26, s26, 0x2000
	s_addc_u32 s27, s27, 0
	global_load_dwordx4 v[60:63], v1, s[26:27]
	s_add_u32 s26, s26, 0x2000
	s_addc_u32 s27, s27, 0
	global_load_dwordx4 v[64:67], v1, s[26:27]
	s_add_u32 s26, s26, 0x2000
	s_addc_u32 s27, s27, 0
	global_load_dwordx4 v[68:71], v1, s[26:27]
	s_add_u32 s26, s26, 0x2000
	s_addc_u32 s27, s27, 0
	global_load_dwordx4 v[72:75], v1, s[26:27]
	s_add_u32 s26, s26, 0x2000
	s_addc_u32 s27, s27, 0
	global_load_dwordx4 v[76:79], v1, s[26:27]
	s_add_u32 s26, s26, 0x2000
	s_addc_u32 s27, s27, 0
	global_load_dwordx4 v[80:83], v1, s[26:27]
	s_add_u32 s26, s26, 0x2000
	s_addc_u32 s27, s27, 0
	global_load_dwordx4 v[84:87], v1, s[26:27]
	s_add_u32 s26, s26, 0x2000
	s_addc_u32 s27, s27, 0
	global_load_dwordx4 v[88:91], v1, s[26:27]
	s_add_u32 s26, s26, 0x2000
	s_addc_u32 s27, s27, 0
	global_load_dwordx4 v[92:95], v1, s[26:27]
	s_add_u32 s26, s26, 0x2000
	s_addc_u32 s27, s27, 0
	global_load_dwordx4 v[96:99], v1, s[26:27]
	s_add_u32 s26, s26, 0x2000
	s_addc_u32 s27, s27, 0
	global_load_dwordx4 v[100:103], v1, s[26:27]
	s_add_u32 s26, s26, 0x2000
	s_addc_u32 s27, s27, 0
	global_load_dwordx4 v[104:107], v1, s[26:27]
	s_mov_b64 s[26:27], s[24:25]
	s_waitcnt vmcnt(16)
	v_fmamk_f32 v12, v12, 0x39800000, v10
	v_fmamk_f32 v14, v14, 0x39800000, v10
	v_fmamk_f32 v16, v16, 0x39800000, v10
	v_fmamk_f32 v18, v18, 0x39800000, v10
	v_fmamk_f32 v20, v20, 0x39800000, v10
	v_fmamk_f32 v22, v22, 0x39800000, v10
	v_fmamk_f32 v24, v24, 0x39800000, v10
	v_fmamk_f32 v26, v26, 0x39800000, v10
	v_rsq_f32_e32 v12, v12
	v_rsq_f32_e32 v14, v14
	v_rsq_f32_e32 v16, v16
	v_rsq_f32_e32 v18, v18
	v_rsq_f32_e32 v20, v20
	v_rsq_f32_e32 v22, v22
	v_rsq_f32_e32 v24, v24
	v_rsq_f32_e32 v26, v26
	s_nop 0
	s_waitcnt vmcnt(15)
	v_pk_mul_f32 v[44:45], v[44:45], v[12:13] op_sel_hi:[1,0]
	v_pk_mul_f32 v[46:47], v[46:47], v[12:13] op_sel_hi:[1,0]
	v_pk_mul_f32 v[44:45], v[44:45], v[6:7]
	v_pk_mul_f32 v[46:47], v[46:47], v[8:9]
	global_store_dwordx4 v1, v[44:47], s[26:27]
	s_add_u32 s26, s26, 0x2000
	s_addc_u32 s27, s27, 0
	s_waitcnt vmcnt(15)
	v_pk_mul_f32 v[48:49], v[48:49], v[12:13] op_sel_hi:[1,0]
	v_pk_mul_f32 v[50:51], v[50:51], v[12:13] op_sel_hi:[1,0]
	v_pk_mul_f32 v[48:49], v[48:49], v[110:111]
	v_pk_mul_f32 v[50:51], v[50:51], v[112:113]
	global_store_dwordx4 v1, v[48:51], s[26:27]
	s_add_u32 s26, s26, 0x2000
	s_addc_u32 s27, s27, 0
	s_waitcnt vmcnt(15)
	v_pk_mul_f32 v[52:53], v[52:53], v[14:15] op_sel_hi:[1,0]
	v_pk_mul_f32 v[54:55], v[54:55], v[14:15] op_sel_hi:[1,0]
	v_pk_mul_f32 v[52:53], v[52:53], v[6:7]
	v_pk_mul_f32 v[54:55], v[54:55], v[8:9]
	global_store_dwordx4 v1, v[52:55], s[26:27]
	s_add_u32 s26, s26, 0x2000
	s_addc_u32 s27, s27, 0
	s_waitcnt vmcnt(15)
; __device__ __forceinline__ void ph_final_norm(float* H, const float* __restrict__ rowss, const float* __restrict__ g, size_t gt, size_t NGT) {
;     const size_t n4 = (size_t)SEQ * DM / 4;
;     f32x4* h4 = (f32x4*)H;
;     for (size_t i0 = gt; i0 < n4; i0 += 8 * NGT) {
;         f32x4 v[8]; float rs[8];
; #pragma unroll
;         for (int k = 0; k < 8; ++k) { const size_t i = i0 + k * NGT; v[k] = h4[i]; rs[k] = rowss[i >> 10]; }
; #pragma unroll
;         for (int k = 0; k < 8; ++k) { const size_t i = i0 + k * NGT; const f32x4 gg = ((const f32x4*)g)[i & 1023]; h4[i] = v[k] * rsqrtf(rs[k] * (1.f / DM) + EPS) * gg; }
;     }
; }
	v_pk_mul_f32 v[56:57], v[56:57], v[14:15] op_sel_hi:[1,0]
	v_pk_mul_f32 v[58:59], v[58:59], v[14:15] op_sel_hi:[1,0]
	v_pk_mul_f32 v[56:57], v[56:57], v[110:111]
	v_pk_mul_f32 v[58:59], v[58:59], v[112:113]
	global_store_dwordx4 v1, v[56:59], s[26:27]
	s_add_u32 s26, s26, 0x2000
	s_addc_u32 s27, s27, 0
	s_waitcnt vmcnt(15)
	v_pk_mul_f32 v[60:61], v[60:61], v[16:17] op_sel_hi:[1,0]
	v_pk_mul_f32 v[62:63], v[62:63], v[16:17] op_sel_hi:[1,0]
	v_pk_mul_f32 v[60:61], v[60:61], v[6:7]
	v_pk_mul_f32 v[62:63], v[62:63], v[8:9]
	global_store_dwordx4 v1, v[60:63], s[26:27]
	s_add_u32 s26, s26, 0x2000
	s_addc_u32 s27, s27, 0
	s_waitcnt vmcnt(15)
	v_pk_mul_f32 v[64:65], v[64:65], v[16:17] op_sel_hi:[1,0]
	v_pk_mul_f32 v[66:67], v[66:67], v[16:17] op_sel_hi:[1,0]
	v_pk_mul_f32 v[64:65], v[64:65], v[110:111]
	v_pk_mul_f32 v[66:67], v[66:67], v[112:113]
	global_store_dwordx4 v1, v[64:67], s[26:27]
	s_add_u32 s26, s26, 0x2000
	s_addc_u32 s27, s27, 0
	s_waitcnt vmcnt(15)
	v_pk_mul_f32 v[68:69], v[68:69], v[18:19] op_sel_hi:[1,0]
	v_pk_mul_f32 v[70:71], v[70:71], v[18:19] op_sel_hi:[1,0]
	v_pk_mul_f32 v[68:69], v[68:69], v[6:7]
	v_pk_mul_f32 v[70:71], v[70:71], v[8:9]
	global_store_dwordx4 v1, v[68:71], s[26:27]
	s_add_u32 s26, s26, 0x2000
	s_addc_u32 s27, s27, 0
	s_waitcnt vmcnt(15)
	v_pk_mul_f32 v[72:73], v[72:73], v[18:19] op_sel_hi:[1,0]
	v_pk_mul_f32 v[74:75], v[74:75], v[18:19] op_sel_hi:[1,0]
	v_pk_mul_f32 v[72:73], v[72:73], v[110:111]
	v_pk_mul_f32 v[74:75], v[74:75], v[112:113]
	global_store_dwordx4 v1, v[72:75], s[26:27]
	s_add_u32 s26, s26, 0x2000
	s_addc_u32 s27, s27, 0
	s_waitcnt vmcnt(15)
	v_pk_mul_f32 v[76:77], v[76:77], v[20:21] op_sel_hi:[1,0]
	v_pk_mul_f32 v[78:79], v[78:79], v[20:21] op_sel_hi:[1,0]
	v_pk_mul_f32 v[76:77], v[76:77], v[6:7]
	v_pk_mul_f32 v[78:79], v[78:79], v[8:9]
	global_store_dwordx4 v1, v[76:79], s[26:27]
	s_add_u32 s26, s26, 0x2000
	s_addc_u32 s27, s27, 0
	s_waitcnt vmcnt(15)
	v_pk_mul_f32 v[80:81], v[80:81], v[20:21] op_sel_hi:[1,0]
	v_pk_mul_f32 v[82:83], v[82:83], v[20:21] op_sel_hi:[1,0]
	v_pk_mul_f32 v[80:81], v[80:81], v[110:111]
	v_pk_mul_f32 v[82:83], v[82:83], v[112:113]
	global_store_dwordx4 v1, v[80:83], s[26:27]
	s_add_u32 s26, s26, 0x2000
	s_addc_u32 s27, s27, 0
	s_waitcnt vmcnt(15)
	v_pk_mul_f32 v[84:85], v[84:85], v[22:23] op_sel_hi:[1,0]
	v_pk_mul_f32 v[86:87], v[86:87], v[22:23] op_sel_hi:[1,0]
	v_pk_mul_f32 v[84:85], v[84:85], v[6:7]
	v_pk_mul_f32 v[86:87], v[86:87], v[8:9]
	global_store_dwordx4 v1, v[84:87], s[26:27]
	s_add_u32 s26, s26, 0x2000
	s_addc_u32 s27, s27, 0
	s_waitcnt vmcnt(15)
	v_pk_mul_f32 v[88:89], v[88:89], v[22:23] op_sel_hi:[1,0]
	v_pk_mul_f32 v[90:91], v[90:91], v[22:23] op_sel_hi:[1,0]
	v_pk_mul_f32 v[88:89], v[88:89], v[110:111]
	v_pk_mul_f32 v[90:91], v[90:91], v[112:113]
	global_store_dwordx4 v1, v[88:91], s[26:27]
	s_add_u32 s26, s26, 0x2000
	s_addc_u32 s27, s27, 0
	s_waitcnt vmcnt(15)
	v_pk_mul_f32 v[92:93], v[92:93], v[24:25] op_sel_hi:[1,0]
	v_pk_mul_f32 v[94:95], v[94:95], v[24:25] op_sel_hi:[1,0]
	v_pk_mul_f32 v[92:93], v[92:93], v[6:7]
	v_pk_mul_f32 v[94:95], v[94:95], v[8:9]
	global_store_dwordx4 v1, v[92:95], s[26:27]
	s_add_u32 s26, s26, 0x2000
	s_addc_u32 s27, s27, 0
	s_waitcnt vmcnt(15)
	v_pk_mul_f32 v[96:97], v[96:97], v[24:25] op_sel_hi:[1,0]
	v_pk_mul_f32 v[98:99], v[98:99], v[24:25] op_sel_hi:[1,0]
	v_pk_mul_f32 v[96:97], v[96:97], v[110:111]
	v_pk_mul_f32 v[98:99], v[98:99], v[112:113]
	global_store_dwordx4 v1, v[96:99], s[26:27]
	s_add_u32 s26, s26, 0x2000
	s_addc_u32 s27, s27, 0
	s_waitcnt vmcnt(15)
	v_pk_mul_f32 v[100:101], v[100:101], v[26:27] op_sel_hi:[1,0]
	v_pk_mul_f32 v[102:103], v[102:103], v[26:27] op_sel_hi:[1,0]
	v_pk_mul_f32 v[100:101], v[100:101], v[6:7]
	v_pk_mul_f32 v[102:103], v[102:103], v[8:9]
	global_store_dwordx4 v1, v[100:103], s[26:27]
	s_add_u32 s26, s26, 0x2000
	s_addc_u32 s27, s27, 0
	s_waitcnt vmcnt(15)
	v_pk_mul_f32 v[104:105], v[104:105], v[26:27] op_sel_hi:[1,0]
	v_pk_mul_f32 v[106:107], v[106:107], v[26:27] op_sel_hi:[1,0]
	v_pk_mul_f32 v[104:105], v[104:105], v[110:111]
	v_pk_mul_f32 v[106:107], v[106:107], v[112:113]
	global_store_dwordx4 v1, v[104:107], s[26:27]
	s_add_u32 s24, s24, 0x20000
	s_addc_u32 s25, s25, 0
	s_add_u32 s20, s20, 32
	s_addc_u32 s21, s21, 0
	s_add_i32 s22, s22, 1
	s_cmp_lt_u32 s22, 8
	s_cbranch_scc1 .Lp9_loop
	s_branch .LBB0_1538
